# P4 task loop: task-table entry fetched with s_load_dword (lgkmcnt wait) instead of a vector load + vmcnt(0) that also drained the previous task's stores
# speedup vs baseline: 1.0014x; 1.0014x over previous
; #define LAS __attribute__((address_space(3)))
; DI void fs_reset(FState& st) { st.o0 = f16zero(); st.o1 = f16zero(); st.m = NINF; st.l = 0.f; }
; DI void dsa_task(LAS unsigned char* lds, const bf16_t* Z, const unsigned* dmask, bf16_t* YB, int b, int qi, int tid, int wave, int lane) {
;     const int r32 = lane & 31, h = lane >> 5;
;     const int tok = 32 * qi + 4 * wave + (r32 >> 3), head = r32 & 7;
;     const size_t grow = (size_t)b * SEQ + tok;
;     const bf16_t* zr = Z + grow * NZ;
;     bf16x8 qf[4];
; #pragma unroll
;     for (int s = 0; s < 4; ++s) qf[s] = *(const bf16x8*)(zr + ZC_QB + head * 64 + 16 * s + 8 * h);
;     const unsigned* dmw = dmask + ((size_t)b * SEQ + 32 * qi + 4 * wave) * 64;
;     FState st, sb; fs_reset(st); fs_reset(sb);
;     const int ntot = (qi >> 1) + 1, npair = (ntot + 1) >> 1;
;     const int skey = tid >> 3, sch = tid & 7;
;     const bf16_t* srow = Z + ((size_t)b * SEQ + skey) * NZ;
;     const int kch = (sch ^ ((skey >> 1) & 7)) * 8, vch = (sch ^ (((skey >> 1) & 1) << 2)) * 8;
;     const int wbase = wave * 1024;
;     ...
;     u32x4 wq0 = *(const u32x4*)(dmw), wq1 = *(const u32x4*)(dmw + 64), wq2 = *(const u32x4*)(dmw + 128), wq3 = *(const u32x4*)(dmw + 192);
; __global__ void __launch_bounds__(NTHR, 2) fwd_kernel(Args a) {
;     ...
;     for (int r = 0; r * G < 2048; ++r) {
;         const int idx = r * G + ((r & 1) ? G - 1 - (int)blockIdx.x : (int)blockIdx.x);
;         if (idx >= 2048) continue;
;         const unsigned e = TASKTAB[idx]; const int k = (int)(e & 255u), bb = (int)(e >> 8);
;         int tid_ = threadIdx.x; asm volatile("" : "+v"(tid_));
;         const int lane_ = tid_ & 63;
;         if (k < 32) { if (EN_WIN || EN_SLC || EN_CMP) nsa_task(lds, Z, SELM, OCMP, YA, bb >> 1, bb & 1, k, tid_, wave, lane_); }
;         else { if (EN_DSA) dsa_task(lds, Z, DMASK, YB, bb, k - 32, tid_, wave, lane_); }
.LBB0_715:
	s_bitcmp0_b32 s67, 0
	s_cselect_b32 s5, s2, s20
	s_add_i32 s4, s5, s4
	s_cmpk_gt_i32 s4, 0x7ff
	s_cbranch_scc1 .LBB0_714
	s_ashr_i32 s5, s4, 31
	s_lshl_b64 s[4:5], s[4:5], 2
	s_add_u32 s4, s42, s4
	s_addc_u32 s5, s43, s5
	s_load_dword s70, s[4:5], 0x0
	v_mov_b32_e32 v213, v0
	s_mov_b64 s[4:5], -1
	v_and_b32_e32 v214, 63, v213
	v_and_b32_e32 v215, 31, v213
	v_ashrrev_i32_e32 v194, 3, v213
	v_ashrrev_i32_e32 v206, 4, v213
	v_lshrrev_b32_e32 v4, 1, v213
	v_bfe_u32 v5, v213, 1, 3
	v_lshrrev_b32_e32 v6, 3, v213
	v_bfe_u32 v7, v213, 2, 2
	v_lshrrev_b32_e32 v210, 5, v214
	v_lshlrev_b32_e32 v8, 3, v214
	v_lshlrev_b32_e32 v9, 1, v214
	v_and_b32_e32 v169, 7, v213
	v_ashrrev_i32_e32 v195, 31, v194
	v_xor_b32_e32 v205, v206, v213
	v_lshlrev_b32_e32 v201, 7, v215
	v_and_or_b32 v211, v6, 4, v7
	v_lshlrev_b32_e32 v164, 4, v210
	v_bitop3_b32 v207, v4, v210, 7 bitop3:0x6c
	v_bitop3_b32 v208, v210, v5, 2 bitop3:0x36
	v_bitop3_b32 v209, v210, v5, 4 bitop3:0x36
	v_bitop3_b32 v212, v210, v5, 6 bitop3:0x36
	v_and_b32_e32 v202, 64, v8
	v_and_b32_e32 v203, 32, v9
	v_and_b32_e32 v204, 24, v8
	s_waitcnt lgkmcnt(0)
	s_and_b32 s69, s70, 0xff
	s_cmp_gt_u32 s69, 31
	s_cbranch_scc0 .LBB0_736
	s_sub_i32 s10, s69, 32
	s_lshl_b32 s8, s10, 5
	s_lshr_b32 s16, s70, 8
	s_add_i32 s4, s8, s47
	v_bfe_u32 v2, v213, 3, 2
	v_or_b32_e32 v2, s4, v2
	s_lshl_b64 s[4:5], s[16:17], 11
	v_lshl_add_u64 v[166:167], s[4:5], 0, v[2:3]
	v_mov_b64_e32 v[4:5], s[22:23]
	v_mad_u64_u32 v[6:7], s[6:7], v166, s58, v[4:5]
	v_lshlrev_b32_e32 v2, 6, v214
	v_and_b32_e32 v168, 0x1c0, v2
	s_add_u32 s6, s4, s47
	v_mad_u32_u24 v7, v167, s58, v7
	v_lshlrev_b32_e32 v2, 1, v168
	s_addc_u32 s7, s5, 0
	v_lshl_add_u64 v[6:7], v[6:7], 0, v[2:3]
	v_mov_b32_e32 v165, v3
	s_add_u32 s6, s6, s8
	v_lshl_add_u64 v[6:7], v[6:7], 0, v[164:165]
	s_addc_u32 s7, s7, 0
	global_load_dwordx4 v[132:135], v[6:7], off offset:1792
	global_load_dwordx4 v[136:139], v[6:7], off offset:1824
	global_load_dwordx4 v[140:143], v[6:7], off offset:1856
	global_load_dwordx4 v[144:147], v[6:7], off offset:1888
	s_lshl_b64 s[6:7], s[6:7], 8
	v_lshl_add_u64 v[6:7], s[4:5], 0, v[194:195]
	v_lshlrev_b32_e32 v2, 3, v205
	s_add_u32 s8, s21, s6
	v_mad_u64_u32 v[170:171], s[4:5], v6, s58, v[4:5]
	v_and_b32_e32 v20, 56, v2
	v_lshlrev_b32_e32 v2, 2, v206
	s_addc_u32 s9, s68, s7
	s_lshr_b32 s71, s10, 1
	v_mad_i32_i24 v171, v7, s58, v171
	v_bitop3_b32 v10, v2, v169, 4 bitop3:0x6c
	v_lshlrev_b32_e32 v2, 1, v20
	s_add_i32 s11, s71, 2
	v_lshl_add_u64 v[6:7], v[170:171], 0, v[2:3]
	s_mov_b32 m0, s54
	s_lshr_b32 s72, s11, 1
	v_lshl_add_u64 v[6:7], v[6:7], 0, s[38:39]
	global_load_dwordx4 v[76:79], v3, s[8:9]
	global_load_dwordx4 v[80:83], v3, s[8:9] offset:256
	global_load_dwordx4 v[68:71], v3, s[8:9] offset:512
	global_load_dwordx4 v[72:75], v3, s[8:9] offset:768
	s_cmp_gt_u32 s10, 1
	global_load_lds_dwordx4 v[6:7], off
	v_lshlrev_b32_e32 v6, 4, v10
	v_mov_b32_e32 v7, v3
	s_mov_b32 s51, 0
	s_cselect_b32 s50, 0x88000, 0
	v_lshl_add_u64 v[8:9], v[170:171], 0, v[6:7]
	v_lshl_add_u64 v[4:5], v[170:171], 0, s[50:51]
	v_lshl_add_u64 v[8:9], v[8:9], 0, s[44:45]
	s_mov_b32 m0, s59
	v_lshlrev_b32_e32 v22, 3, v10
	global_load_lds_dwordx4 v[8:9], off
	v_lshl_add_u64 v[8:9], v[4:5], 0, v[2:3]
	v_lshl_add_u64 v[8:9], v[8:9], 0, s[38:39]
	s_mov_b32 m0, s60
	v_lshl_add_u64 v[4:5], v[4:5], 0, v[6:7]
	global_load_lds_dwordx4 v[8:9], off
	v_lshl_add_u64 v[4:5], v[4:5], 0, s[44:45]
	s_mov_b32 m0, s61
	v_lshlrev_b32_e32 v2, 7, v211
	global_load_lds_dwordx4 v[4:5], off
	v_mad_i64_i32 v[4:5], s[4:5], v194, s58, 0
	v_or3_b32 v219, v2, v203, v204
	v_mad_u64_u32 v[4:5], s[4:5], s16, v1, v[4:5]
	v_bitop3_b32 v2, v206, 7, v213 bitop3:0x48
	v_lshl_or_b32 v8, v2, 4, v4
	v_mov_b32_e32 v9, v5
	v_or_b32_e32 v4, v4, v6
	v_mov_b32_e32 v18, v3
	v_mov_b32_e32 v19, v3
	v_lshl_add_u64 v[174:175], s[26:27], 0, v[8:9]
	v_lshl_add_u64 v[176:177], s[28:29], 0, v[4:5]
	s_add_u32 s52, s56, s6
	v_mov_b32_e32 v187, v186
	v_mov_b32_e32 v4, v3
	v_mov_b32_e32 v5, v3
	v_mov_b32_e32 v6, v3
	v_mov_b32_e32 v8, v3
	v_mov_b32_e32 v9, v3
	v_mov_b32_e32 v10, v3
	v_mov_b32_e32 v11, v3
	v_mov_b32_e32 v12, v3
	v_mov_b32_e32 v13, v3
	v_mov_b32_e32 v14, v3
	v_mov_b32_e32 v15, v3
	v_mov_b32_e32 v16, v3
	v_mov_b32_e32 v17, v3
	v_lshlrev_b32_e32 v2, 1, v20
	v_lshlrev_b32_e32 v178, 1, v22
	v_mov_b64_e32 v[50:51], v[18:19]
	v_mov_b64_e32 v[34:35], v[18:19]
	v_mov_b64_e32 v[66:67], v[18:19]
	v_cmp_gt_u32_e64 s[10:11], 32, v214
	v_lshlrev_b32_e32 v165, 4, v207
	v_lshlrev_b32_e32 v216, 4, v208
	v_lshlrev_b32_e32 v217, 4, v209
	v_lshlrev_b32_e32 v218, 4, v212
	v_sub_u32_e32 v220, 0, v202
	s_addc_u32 s53, s57, s7
	v_mov_b32_e32 v172, v3
	v_mov_b32_e32 v173, v3
	s_mov_b32 s16, 0x8000
	s_mov_b32 s50, s51
	v_mov_b64_e32 v[48:49], v[16:17]
	v_mov_b64_e32 v[46:47], v[14:15]
	v_mov_b64_e32 v[44:45], v[12:13]
	v_mov_b64_e32 v[42:43], v[10:11]
	v_mov_b64_e32 v[40:41], v[8:9]
	v_mov_b64_e32 v[38:39], v[6:7]
	v_mov_b64_e32 v[36:37], v[4:5]
	s_waitcnt vmcnt(0)
	v_mov_b64_e32 v[162:163], v[78:79]
	v_mov_b64_e32 v[158:159], v[82:83]
	v_mov_b64_e32 v[154:155], v[70:71]
	v_mov_b64_e32 v[150:151], v[74:75]
	v_mov_b64_e32 v[32:33], v[16:17]
	v_mov_b64_e32 v[30:31], v[14:15]
	v_mov_b64_e32 v[28:29], v[12:13]
	v_mov_b64_e32 v[26:27], v[10:11]
	v_mov_b64_e32 v[24:25], v[8:9]
	v_mov_b64_e32 v[22:23], v[6:7]
	v_mov_b64_e32 v[20:21], v[4:5]
	v_mov_b64_e32 v[64:65], v[16:17]
	v_mov_b64_e32 v[62:63], v[14:15]
	v_mov_b64_e32 v[60:61], v[12:13]
	v_mov_b64_e32 v[58:59], v[10:11]
	v_mov_b64_e32 v[56:57], v[8:9]
	v_mov_b64_e32 v[54:55], v[6:7]
	v_mov_b64_e32 v[52:53], v[4:5]
	v_mov_b64_e32 v[180:181], v[186:187]
	v_mov_b64_e32 v[148:149], v[72:73]
	v_mov_b64_e32 v[152:153], v[68:69]
	v_mov_b64_e32 v[156:157], v[80:81]
	v_mov_b64_e32 v[160:161], v[76:77]
	v_mov_b32_e32 v86, v214
	v_mov_b32_e32 v90, 0
	v_cmp_gt_u32_e32 vcc, 32, v86
	v_mov_b32_e32 v84, 0
	v_mov_b32_e32 v85, 0
	s_and_saveexec_b64 s[4:5], vcc
	s_cbranch_execz .Ldsa_ef_done
	v_lshrrev_b32_e32 v85, 3, v86
	v_cmp_gt_u32_e32 vcc, 8, v86
	s_nop 1
	v_cndmask_b32_e32 v84, 0, v200, vcc
	v_cmp_eq_u32_e32 vcc, 1, v85
	s_nop 1
	v_cndmask_b32_e64 v86, 0, 1.0, vcc
	v_cmp_eq_u32_e32 vcc, 2, v85
	v_or_b32_e32 v84, v86, v84
	s_nop 0
	v_cndmask_b32_e32 v86, 0, v200, vcc
	v_cmp_eq_u32_e32 vcc, 3, v85
	s_nop 1
	v_cndmask_b32_e64 v85, 0, 1.0, vcc
	v_or_b32_e32 v85, v86, v85
